# residual GEMM epilogue: row sum-of-squares cross-lane reduction with v_permlane16/32_swap instead of two ds_bpermute round trips per row block
# speedup vs baseline: 1.0106x; 1.0106x over previous
; __device__ __forceinline__ unsigned cvt_pk_bf16(float lo, float hi) { unsigned r; asm("v_cvt_pk_bf16_f32 %0, %1, %2" : "=v"(r) : "v"(lo), "v"(hi)); return r; }
; __device__ __forceinline__ void unpack8(const u32x4 w, float (&f)[8]) { f[0] = bf_lo(w.x); f[1] = bf_hi(w.x); f[2] = bf_lo(w.y); f[3] = bf_hi(w.y); f[4] = bf_lo(w.z); f[5] = bf_hi(w.z); f[6] = bf_lo(w.w); f[7] = bf_hi(w.w); }
;     __device__ __forceinline__ void operator()(const f32x4 (&acc)[2][2][4][2], const Unit& u, int wr, int wc, int fr, int fq) const {
;     ...
;         const int row0 = u.pm * BM + wr * 64 + fr, col0 = u.pn * BM + wc * 32 + 8 * fq;
;         u32x4 xo[2][4][2];
; #pragma unroll
;         for (int ai = 0; ai < 2; ++ai)
; #pragma unroll
;             for (int m = 0; m < 4; ++m) { const size_t off = (size_t)(row0 + ai * HALF + m * 16) * D + col0;
; #pragma unroll
;                 for (int bj = 0; bj < 2; ++bj) xo[ai][m][bj] = *(const u32x4*)(xb + off + bj * HALF); }
; #pragma unroll
;         for (int ai = 0; ai < 2; ++ai) {
; #pragma unroll
;             for (int m = 0; m < 4; ++m) { const int row = row0 + ai * HALF + m * 16; const size_t off = (size_t)row * D + col0; float sq = 0.f;
; #pragma unroll
;                 for (int bj = 0; bj < 2; ++bj) {
;                     float xf[8]; unpack8(xo[ai][m][bj], xf);
;                     const f32x4 x0 = (f32x4){xf[0], xf[1], xf[2], xf[3]} + acc[ai][bj][m][0], x1 = (f32x4){xf[4], xf[5], xf[6], xf[7]} + acc[ai][bj][m][1];
;                     sq += (x0[0] * x0[0] + x0[1] * x0[1]) + (x0[2] * x0[2] + x0[3] * x0[3]) + (x1[0] * x1[0] + x1[1] * x1[1]) + (x1[2] * x1[2] + x1[3] * x1[3]);
;                     u32x4 w; w.x = cvt_pk_bf16(x0[0], x0[1]); w.y = cvt_pk_bf16(x0[2], x0[3]); w.z = cvt_pk_bf16(x1[0], x1[1]); w.w = cvt_pk_bf16(x1[2], x1[3]);
;                     *(u32x4*)(xb + off + bj * HALF) = w; }
;                 sq += __shfl_xor(sq, 16); sq += __shfl_xor(sq, 32); if (fq == 0) ssn[(size_t)row * 16 + u.pn * 4 + wc] = sq; }
.LBB0_302:
	s_lshl_b32 s0, s57, 8
	s_add_i32 s0, s0, s47
	v_mbcnt_lo_u32_b32 v195, -1, 0
	v_mbcnt_hi_u32_b32 v195, -1, v195
	v_readlane_b32 s36, v254, 57
	v_and_or_b32 v242, v195, 15, s0
	s_lshl_b32 s0, s56, 8
	v_ashrrev_i32_e32 v130, 1, v195
	s_or_b32 s0, s0, s48
	v_and_b32_e32 v130, -8, v130
	v_add_u32_e32 v212, s0, v130
	v_ashrrev_i32_e32 v213, 31, v212
	v_lshlrev_b64 v[244:245], 1, v[212:213]
	v_readlane_b32 s37, v254, 58
	v_ashrrev_i32_e32 v243, 31, v242
	v_lshlrev_b64 v[246:247], 11, v[242:243]
	v_lshl_add_u64 v[130:131], s[36:37], 0, v[244:245]
	v_lshl_add_u64 v[132:133], v[130:131], 0, v[246:247]
	global_load_dwordx4 v[190:193], v[132:133], off
	global_load_dwordx4 v[186:189], v[132:133], off offset:256
	v_or_b32_e32 v238, 16, v242
	v_ashrrev_i32_e32 v239, 31, v238
	v_or_b32_e32 v234, 32, v242
	v_lshlrev_b64 v[240:241], 11, v[238:239]
	v_ashrrev_i32_e32 v235, 31, v234
	v_or_b32_e32 v230, 48, v242
	v_lshl_add_u64 v[132:133], v[130:131], 0, v[240:241]
	v_lshlrev_b64 v[236:237], 11, v[234:235]
	v_ashrrev_i32_e32 v231, 31, v230
	v_add_u32_e32 v226, 0x80, v242
	global_load_dwordx4 v[182:185], v[132:133], off
	global_load_dwordx4 v[178:181], v[132:133], off offset:256
	v_lshl_add_u64 v[132:133], v[130:131], 0, v[236:237]
	v_lshlrev_b64 v[232:233], 11, v[230:231]
	v_ashrrev_i32_e32 v227, 31, v226
	v_add_u32_e32 v222, 0x90, v242
	global_load_dwordx4 v[174:177], v[132:133], off
	global_load_dwordx4 v[170:173], v[132:133], off offset:256
	v_lshl_add_u64 v[132:133], v[130:131], 0, v[232:233]
	v_lshlrev_b64 v[228:229], 11, v[226:227]
	v_ashrrev_i32_e32 v223, 31, v222
	v_add_u32_e32 v218, 0xa0, v242
	v_add_u32_e32 v214, 0xb0, v242
	global_load_dwordx4 v[166:169], v[132:133], off
	global_load_dwordx4 v[162:165], v[132:133], off offset:256
	v_lshl_add_u64 v[132:133], v[130:131], 0, v[228:229]
	v_lshlrev_b64 v[224:225], 11, v[222:223]
	v_ashrrev_i32_e32 v219, 31, v218
	v_ashrrev_i32_e32 v215, 31, v214
	global_load_dwordx4 v[158:161], v[132:133], off
	global_load_dwordx4 v[154:157], v[132:133], off offset:256
	v_lshl_add_u64 v[132:133], v[130:131], 0, v[224:225]
	v_lshlrev_b64 v[220:221], 11, v[218:219]
	v_lshlrev_b64 v[216:217], 11, v[214:215]
	global_load_dwordx4 v[150:153], v[132:133], off
	global_load_dwordx4 v[146:149], v[132:133], off offset:256
	v_lshl_add_u64 v[132:133], v[130:131], 0, v[220:221]
	v_lshl_add_u64 v[130:131], v[130:131], 0, v[216:217]
	global_load_dwordx4 v[142:145], v[132:133], off
	global_load_dwordx4 v[134:137], v[132:133], off offset:256
	global_load_dwordx4 v[138:141], v[130:131], off
	s_nop 0
	global_load_dwordx4 v[130:133], v[130:131], off offset:256
	s_lshl_b32 s34, s56, 2
	v_cmp_gt_u32_e32 vcc, 16, v195
	s_ashr_i32 s35, s34, 31
	s_waitcnt vmcnt(0) lgkmcnt(0)
	v_lshlrev_b32_e32 v196, 16, v190
	v_and_b32_e32 v197, 0xffff0000, v190
	v_lshlrev_b32_e32 v190, 16, v191
	v_and_b32_e32 v191, 0xffff0000, v191
	v_pk_add_f32 v[190:191], v[124:125], v[190:191]
	v_pk_add_f32 v[122:123], v[122:123], v[196:197]
	v_lshlrev_b32_e32 v198, 16, v192
	v_and_b32_e32 v199, 0xffff0000, v192
	v_mul_f32_e32 v124, v123, v123
	v_mul_f32_e32 v125, v191, v191
	v_pk_add_f32 v[126:127], v[126:127], v[198:199]
	v_fmac_f32_e32 v124, v122, v122
	v_fmac_f32_e32 v125, v190, v190
	v_lshlrev_b32_e32 v192, 16, v193
	v_and_b32_e32 v193, 0xffff0000, v193
	v_add_f32_e32 v124, v124, v125
	v_mul_f32_e32 v125, v127, v127
	v_pk_add_f32 v[128:129], v[128:129], v[192:193]
	v_fmac_f32_e32 v125, v126, v126
	v_add_f32_e32 v124, v125, v124
	v_mul_f32_e32 v125, v129, v129
	v_fmac_f32_e32 v125, v128, v128
	v_add_f32_e32 v192, v125, v124
	v_cvt_pk_bf16_f32 v124, v122, v123
	v_lshl_add_u64 v[122:123], s[36:37], 0, v[246:247]
	v_cvt_pk_bf16_f32 v125, v190, v191
	v_cvt_pk_bf16_f32 v126, v126, v127
	v_cvt_pk_bf16_f32 v127, v128, v129
	v_lshl_add_u64 v[122:123], v[122:123], 0, v[244:245]
	global_store_dwordx4 v[122:123], v[124:127], off
	v_lshlrev_b32_e32 v128, 16, v188
	v_and_b32_e32 v129, 0xffff0000, v188
	v_lshlrev_b32_e32 v124, 16, v186
	v_and_b32_e32 v125, 0xffff0000, v186
	v_lshlrev_b32_e32 v126, 16, v187
	v_and_b32_e32 v127, 0xffff0000, v187
	v_lshlrev_b32_e32 v186, 16, v189
	v_and_b32_e32 v187, 0xffff0000, v189
	v_pk_add_f32 v[120:121], v[120:121], v[126:127]
	v_pk_add_f32 v[118:119], v[118:119], v[124:125]
	v_pk_add_f32 v[124:125], v[116:117], v[186:187]
	v_pk_add_f32 v[116:117], v[114:115], v[128:129]
	v_mul_f32_e32 v114, v119, v119
	v_mul_f32_e32 v115, v121, v121
	v_fmac_f32_e32 v114, v118, v118
	v_fmac_f32_e32 v115, v120, v120
	v_add_f32_e32 v114, v114, v115
	v_mul_f32_e32 v115, v117, v117
	v_fmac_f32_e32 v115, v116, v116
	v_add_f32_e32 v114, v115, v114
	v_mul_f32_e32 v115, v125, v125
	v_fmac_f32_e32 v115, v124, v124
	v_add_f32_e32 v114, v115, v114
	v_cvt_pk_bf16_f32 v115, v120, v121
	v_add_f32_e32 v126, v192, v114
	v_cvt_pk_bf16_f32 v114, v118, v119
	v_cvt_pk_bf16_f32 v116, v116, v117
	v_cvt_pk_bf16_f32 v117, v124, v125
	global_store_dwordx4 v[122:123], v[114:117], off offset:256
	s_nop 1
	v_and_b32_e32 v115, 64, v250
	v_xor_b32_e32 v114, 16, v250
	v_add_u32_e32 v115, 64, v115
	v_cmp_lt_i32_e64 s[6:7], v114, v115
	v_xor_b32_e32 v117, 32, v250
	s_nop 0
	v_cndmask_b32_e64 v114, v250, v114, s[6:7]
	v_lshlrev_b32_e32 v114, 2, v114
	v_mov_b32_e32 v116, v126
	s_nop 1
	v_permlane16_swap_b32_e32 v126, v116
	v_cmp_lt_i32_e64 s[6:7], v117, v115
	s_waitcnt lgkmcnt(0)
	v_add_f32_e32 v116, v126, v116
	v_cndmask_b32_e64 v115, v250, v117, s[6:7]
	v_lshlrev_b32_e32 v115, 2, v115
	v_mov_b32_e32 v117, v116
	s_nop 1
	v_permlane32_swap_b32_e32 v116, v117
	s_and_saveexec_b64 s[0:1], vcc
	s_cbranch_execz .LBB0_304
	s_waitcnt lgkmcnt(0)
	v_add_f32_e32 v118, v116, v117
	v_lshlrev_b64 v[116:117], 6, v[242:243]
	v_lshl_add_u64 v[116:117], s[22:23], 0, v[116:117]
	v_lshl_add_u64 v[116:117], s[34:35], 2, v[116:117]
	s_lshl_b32 s92, s45, 2
	v_lshl_add_u64 v[116:117], v[116:117], 0, s[92:93]
	global_store_dword v[116:117], v118, off
; __device__ __forceinline__ unsigned cvt_pk_bf16(float lo, float hi) { unsigned r; asm("v_cvt_pk_bf16_f32 %0, %1, %2" : "=v"(r) : "v"(lo), "v"(hi)); return r; }
; __device__ __forceinline__ void unpack8(const u32x4 w, float (&f)[8]) { f[0] = bf_lo(w.x); f[1] = bf_hi(w.x); f[2] = bf_lo(w.y); f[3] = bf_hi(w.y); f[4] = bf_lo(w.z); f[5] = bf_hi(w.z); f[6] = bf_lo(w.w); f[7] = bf_hi(w.w); }
;     __device__ __forceinline__ void operator()(const f32x4 (&acc)[2][2][4][2], const Unit& u, int wr, int wc, int fr, int fq) const {
;     ...
;         for (int ai = 0; ai < 2; ++ai) {
; #pragma unroll
;             for (int m = 0; m < 4; ++m) { const int row = row0 + ai * HALF + m * 16; const size_t off = (size_t)row * D + col0; float sq = 0.f;
; #pragma unroll
;                 for (int bj = 0; bj < 2; ++bj) {
;                     float xf[8]; unpack8(xo[ai][m][bj], xf);
;                     const f32x4 x0 = (f32x4){xf[0], xf[1], xf[2], xf[3]} + acc[ai][bj][m][0], x1 = (f32x4){xf[4], xf[5], xf[6], xf[7]} + acc[ai][bj][m][1];
;                     sq += (x0[0] * x0[0] + x0[1] * x0[1]) + (x0[2] * x0[2] + x0[3] * x0[3]) + (x1[0] * x1[0] + x1[1] * x1[1]) + (x1[2] * x1[2] + x1[3] * x1[3]);
;                     u32x4 w; w.x = cvt_pk_bf16(x0[0], x0[1]); w.y = cvt_pk_bf16(x0[2], x0[3]); w.z = cvt_pk_bf16(x1[0], x1[1]); w.w = cvt_pk_bf16(x1[2], x1[3]);
;                     *(u32x4*)(xb + off + bj * HALF) = w; }
;                 sq += __shfl_xor(sq, 16); sq += __shfl_xor(sq, 32); if (fq == 0) ssn[(size_t)row * 16 + u.pn * 4 + wc] = sq; }
.LBB0_304:
	s_or_b64 exec, exec, s[0:1]
	v_lshlrev_b32_e32 v116, 16, v182
	s_waitcnt lgkmcnt(0)
	v_and_b32_e32 v117, 0xffff0000, v182
	v_lshlrev_b32_e32 v118, 16, v183
	v_and_b32_e32 v119, 0xffff0000, v183
	v_lshlrev_b32_e32 v120, 16, v184
	v_and_b32_e32 v121, 0xffff0000, v184
	v_lshlrev_b32_e32 v122, 16, v185
	v_and_b32_e32 v123, 0xffff0000, v185
	v_pk_add_f32 v[112:113], v[112:113], v[118:119]
	v_pk_add_f32 v[110:111], v[110:111], v[116:117]
	v_pk_add_f32 v[116:117], v[108:109], v[122:123]
	v_pk_add_f32 v[108:109], v[106:107], v[120:121]
	v_mul_f32_e32 v106, v111, v111
	v_mul_f32_e32 v107, v113, v113
	v_fmac_f32_e32 v106, v110, v110
	v_fmac_f32_e32 v107, v112, v112
	v_add_f32_e32 v106, v106, v107
	v_mul_f32_e32 v107, v109, v109
	v_fmac_f32_e32 v107, v108, v108
	v_add_f32_e32 v106, v107, v106
	v_mul_f32_e32 v107, v117, v117
	v_fmac_f32_e32 v107, v116, v116
	v_add_f32_e32 v120, v107, v106
	v_cvt_pk_bf16_f32 v106, v110, v111
	v_cvt_pk_bf16_f32 v107, v112, v113
	v_lshlrev_b32_e32 v110, 16, v178
	v_and_b32_e32 v111, 0xffff0000, v178
	v_lshlrev_b32_e32 v112, 16, v179
	v_and_b32_e32 v113, 0xffff0000, v179
	v_cvt_pk_bf16_f32 v108, v108, v109
	v_cvt_pk_bf16_f32 v109, v116, v117
	v_lshlrev_b32_e32 v116, 16, v180
	v_and_b32_e32 v117, 0xffff0000, v180
	v_pk_add_f32 v[104:105], v[104:105], v[112:113]
	v_pk_add_f32 v[102:103], v[102:103], v[110:111]
	v_pk_add_f32 v[112:113], v[98:99], v[116:117]
	v_mul_f32_e32 v98, v103, v103
	v_mul_f32_e32 v99, v105, v105
	v_fmac_f32_e32 v98, v102, v102
	v_fmac_f32_e32 v99, v104, v104
	v_lshlrev_b32_e32 v118, 16, v181
	v_and_b32_e32 v119, 0xffff0000, v181
	v_add_f32_e32 v98, v98, v99
	v_mul_f32_e32 v99, v113, v113
	v_pk_add_f32 v[110:111], v[100:101], v[118:119]
	v_fmac_f32_e32 v99, v112, v112
	v_add_f32_e32 v98, v99, v98
	v_mul_f32_e32 v99, v111, v111
	v_fmac_f32_e32 v99, v110, v110
	v_add_f32_e32 v98, v99, v98
	v_add_f32_e32 v101, v120, v98
	v_mov_b32_e32 v118, v101
	s_nop 1
	v_permlane16_swap_b32_e32 v101, v118
	v_lshl_add_u64 v[98:99], s[36:37], 0, v[240:241]
	v_lshl_add_u64 v[116:117], v[212:213], 1, v[98:99]
	global_store_dwordx4 v[116:117], v[106:109], off
	v_cvt_pk_bf16_f32 v100, v102, v103
	s_waitcnt lgkmcnt(0)
	v_add_f32_e32 v98, v101, v118
	v_mov_b32_e32 v99, v98
	s_nop 1
	v_permlane32_swap_b32_e32 v98, v99
	v_cvt_pk_bf16_f32 v101, v104, v105
	v_cvt_pk_bf16_f32 v102, v112, v113
	v_cvt_pk_bf16_f32 v103, v110, v111
	global_store_dwordx4 v[116:117], v[100:103], off offset:256
	s_and_saveexec_b64 s[0:1], vcc
	s_cbranch_execz .LBB0_306
	s_waitcnt lgkmcnt(0)
	v_add_f32_e32 v100, v98, v99
	v_lshlrev_b64 v[98:99], 6, v[238:239]
	v_lshl_add_u64 v[98:99], s[22:23], 0, v[98:99]
	v_lshl_add_u64 v[98:99], s[34:35], 2, v[98:99]
	s_lshl_b32 s92, s45, 2
	v_lshl_add_u64 v[98:99], v[98:99], 0, s[92:93]
	global_store_dword v[98:99], v100, off
.LBB0_306:
	s_or_b64 exec, exec, s[0:1]
	v_lshlrev_b32_e32 v98, 16, v174
	s_waitcnt lgkmcnt(0)
	v_and_b32_e32 v99, 0xffff0000, v174
	v_lshlrev_b32_e32 v100, 16, v175
	v_and_b32_e32 v101, 0xffff0000, v175
	v_lshlrev_b32_e32 v102, 16, v176
	v_and_b32_e32 v103, 0xffff0000, v176
	v_lshlrev_b32_e32 v104, 16, v177
	v_and_b32_e32 v105, 0xffff0000, v177
	v_pk_add_f32 v[96:97], v[96:97], v[100:101]
	v_pk_add_f32 v[94:95], v[94:95], v[98:99]
	v_pk_add_f32 v[98:99], v[92:93], v[104:105]
	v_pk_add_f32 v[92:93], v[90:91], v[102:103]
	v_mul_f32_e32 v90, v95, v95
	v_mul_f32_e32 v91, v97, v97
	v_fmac_f32_e32 v90, v94, v94
	v_fmac_f32_e32 v91, v96, v96
	v_add_f32_e32 v90, v90, v91
	v_mul_f32_e32 v91, v93, v93
	v_fmac_f32_e32 v91, v92, v92
	v_add_f32_e32 v90, v91, v90
	v_mul_f32_e32 v91, v99, v99
	v_fmac_f32_e32 v91, v98, v98
	v_add_f32_e32 v102, v91, v90
	v_cvt_pk_bf16_f32 v90, v94, v95
	v_cvt_pk_bf16_f32 v91, v96, v97
	v_lshlrev_b32_e32 v94, 16, v170
	v_and_b32_e32 v95, 0xffff0000, v170
	v_lshlrev_b32_e32 v96, 16, v171
	v_and_b32_e32 v97, 0xffff0000, v171
	v_cvt_pk_bf16_f32 v92, v92, v93
	v_cvt_pk_bf16_f32 v93, v98, v99
	v_lshlrev_b32_e32 v98, 16, v172
	v_and_b32_e32 v99, 0xffff0000, v172
	v_pk_add_f32 v[88:89], v[88:89], v[96:97]
	v_pk_add_f32 v[86:87], v[86:87], v[94:95]
	v_pk_add_f32 v[96:97], v[82:83], v[98:99]
	v_mul_f32_e32 v82, v87, v87
	v_mul_f32_e32 v83, v89, v89
	v_fmac_f32_e32 v82, v86, v86
	v_fmac_f32_e32 v83, v88, v88
	v_lshlrev_b32_e32 v100, 16, v173
	v_and_b32_e32 v101, 0xffff0000, v173
	v_add_f32_e32 v82, v82, v83
	v_mul_f32_e32 v83, v97, v97
	v_pk_add_f32 v[94:95], v[84:85], v[100:101]
	v_fmac_f32_e32 v83, v96, v96
	v_add_f32_e32 v82, v83, v82
	v_mul_f32_e32 v83, v95, v95
	v_fmac_f32_e32 v83, v94, v94
	v_add_f32_e32 v82, v83, v82
	v_add_f32_e32 v85, v102, v82
	v_mov_b32_e32 v100, v85
	s_nop 1
	v_permlane16_swap_b32_e32 v85, v100
	v_lshl_add_u64 v[82:83], s[36:37], 0, v[236:237]
	v_lshl_add_u64 v[98:99], v[212:213], 1, v[82:83]
	global_store_dwordx4 v[98:99], v[90:93], off
	v_cvt_pk_bf16_f32 v84, v86, v87
	s_waitcnt lgkmcnt(0)
	v_add_f32_e32 v82, v85, v100
	v_mov_b32_e32 v83, v82
	s_nop 1
	v_permlane32_swap_b32_e32 v82, v83
	v_cvt_pk_bf16_f32 v85, v88, v89
	v_cvt_pk_bf16_f32 v86, v96, v97
	v_cvt_pk_bf16_f32 v87, v94, v95
	global_store_dwordx4 v[98:99], v[84:87], off offset:256
	s_mov_b64 s[0:1], exec
	s_and_b64 s[6:7], s[0:1], vcc
	v_mov_b64_e32 v[244:245], v[200:201]
	v_mov_b64_e32 v[200:201], 0x400
	v_mov_b64_e32 v[246:247], 0x1ff
	s_mov_b64 exec, s[6:7]
	s_cbranch_execz .LBB0_308
	s_waitcnt lgkmcnt(0)
	v_add_f32_e32 v84, v82, v83
	v_lshlrev_b64 v[82:83], 6, v[234:235]
	v_lshl_add_u64 v[82:83], s[22:23], 0, v[82:83]
	v_lshl_add_u64 v[82:83], s[34:35], 2, v[82:83]
	s_lshl_b32 s92, s45, 2
	v_lshl_add_u64 v[82:83], v[82:83], 0, s[92:93]
	global_store_dword v[82:83], v84, off
; __device__ __forceinline__ unsigned cvt_pk_bf16(float lo, float hi) { unsigned r; asm("v_cvt_pk_bf16_f32 %0, %1, %2" : "=v"(r) : "v"(lo), "v"(hi)); return r; }
; __device__ __forceinline__ void unpack8(const u32x4 w, float (&f)[8]) { f[0] = bf_lo(w.x); f[1] = bf_hi(w.x); f[2] = bf_lo(w.y); f[3] = bf_hi(w.y); f[4] = bf_lo(w.z); f[5] = bf_hi(w.z); f[6] = bf_lo(w.w); f[7] = bf_hi(w.w); }
;     __device__ __forceinline__ void operator()(const f32x4 (&acc)[2][2][4][2], const Unit& u, int wr, int wc, int fr, int fq) const {
;     ...
;         for (int ai = 0; ai < 2; ++ai) {
; #pragma unroll
;             for (int m = 0; m < 4; ++m) { const int row = row0 + ai * HALF + m * 16; const size_t off = (size_t)row * D + col0; float sq = 0.f;
; #pragma unroll
;                 for (int bj = 0; bj < 2; ++bj) {
;                     float xf[8]; unpack8(xo[ai][m][bj], xf);
;                     const f32x4 x0 = (f32x4){xf[0], xf[1], xf[2], xf[3]} + acc[ai][bj][m][0], x1 = (f32x4){xf[4], xf[5], xf[6], xf[7]} + acc[ai][bj][m][1];
;                     sq += (x0[0] * x0[0] + x0[1] * x0[1]) + (x0[2] * x0[2] + x0[3] * x0[3]) + (x1[0] * x1[0] + x1[1] * x1[1]) + (x1[2] * x1[2] + x1[3] * x1[3]);
;                     u32x4 w; w.x = cvt_pk_bf16(x0[0], x0[1]); w.y = cvt_pk_bf16(x0[2], x0[3]); w.z = cvt_pk_bf16(x1[0], x1[1]); w.w = cvt_pk_bf16(x1[2], x1[3]);
;                     *(u32x4*)(xb + off + bj * HALF) = w; }
;                 sq += __shfl_xor(sq, 16); sq += __shfl_xor(sq, 32); if (fq == 0) ssn[(size_t)row * 16 + u.pn * 4 + wc] = sq; }
.LBB0_308:
	s_or_b64 exec, exec, s[0:1]
	v_lshlrev_b32_e32 v82, 16, v166
	s_waitcnt lgkmcnt(0)
	v_and_b32_e32 v83, 0xffff0000, v166
	v_lshlrev_b32_e32 v84, 16, v167
	v_and_b32_e32 v85, 0xffff0000, v167
	v_lshlrev_b32_e32 v86, 16, v168
	v_and_b32_e32 v87, 0xffff0000, v168
	v_lshlrev_b32_e32 v88, 16, v169
	v_and_b32_e32 v89, 0xffff0000, v169
	v_pk_add_f32 v[80:81], v[80:81], v[84:85]
	v_pk_add_f32 v[78:79], v[78:79], v[82:83]
	v_pk_add_f32 v[82:83], v[76:77], v[88:89]
	v_pk_add_f32 v[76:77], v[74:75], v[86:87]
	v_mul_f32_e32 v74, v79, v79
	v_mul_f32_e32 v75, v81, v81
	v_fmac_f32_e32 v74, v78, v78
	v_fmac_f32_e32 v75, v80, v80
	v_add_f32_e32 v74, v74, v75
	v_mul_f32_e32 v75, v77, v77
	v_fmac_f32_e32 v75, v76, v76
	v_add_f32_e32 v74, v75, v74
	v_mul_f32_e32 v75, v83, v83
	v_fmac_f32_e32 v75, v82, v82
	v_add_f32_e32 v86, v75, v74
	v_cvt_pk_bf16_f32 v74, v78, v79
	v_cvt_pk_bf16_f32 v75, v80, v81
	v_lshlrev_b32_e32 v78, 16, v162
	v_and_b32_e32 v79, 0xffff0000, v162
	v_lshlrev_b32_e32 v80, 16, v163
	v_and_b32_e32 v81, 0xffff0000, v163
	v_cvt_pk_bf16_f32 v76, v76, v77
	v_cvt_pk_bf16_f32 v77, v82, v83
	v_lshlrev_b32_e32 v82, 16, v164
	v_and_b32_e32 v83, 0xffff0000, v164
	v_pk_add_f32 v[72:73], v[72:73], v[80:81]
	v_pk_add_f32 v[70:71], v[70:71], v[78:79]
	v_pk_add_f32 v[80:81], v[66:67], v[82:83]
	v_mul_f32_e32 v66, v71, v71
	v_mul_f32_e32 v67, v73, v73
	v_fmac_f32_e32 v66, v70, v70
	v_fmac_f32_e32 v67, v72, v72
	v_lshlrev_b32_e32 v84, 16, v165
	v_and_b32_e32 v85, 0xffff0000, v165
	v_add_f32_e32 v66, v66, v67
	v_mul_f32_e32 v67, v81, v81
	v_pk_add_f32 v[78:79], v[68:69], v[84:85]
	v_fmac_f32_e32 v67, v80, v80
	v_add_f32_e32 v66, v67, v66
	v_mul_f32_e32 v67, v79, v79
	v_fmac_f32_e32 v67, v78, v78
	v_add_f32_e32 v66, v67, v66
	v_add_f32_e32 v69, v86, v66
	v_mov_b32_e32 v84, v69
	s_nop 1
	v_permlane16_swap_b32_e32 v69, v84
	v_lshl_add_u64 v[66:67], s[36:37], 0, v[232:233]
	v_lshl_add_u64 v[82:83], v[212:213], 1, v[66:67]
	global_store_dwordx4 v[82:83], v[74:77], off
	v_cvt_pk_bf16_f32 v68, v70, v71
	s_waitcnt lgkmcnt(0)
	v_add_f32_e32 v66, v69, v84
	v_mov_b32_e32 v67, v66
	s_nop 1
	v_permlane32_swap_b32_e32 v66, v67
	v_cvt_pk_bf16_f32 v69, v72, v73
	v_cvt_pk_bf16_f32 v70, v80, v81
	v_cvt_pk_bf16_f32 v71, v78, v79
	global_store_dwordx4 v[82:83], v[68:71], off offset:256
	s_and_saveexec_b64 s[0:1], vcc
	s_cbranch_execz .LBB0_310
	s_waitcnt lgkmcnt(0)
	v_add_f32_e32 v68, v66, v67
	v_lshlrev_b64 v[66:67], 6, v[230:231]
	v_lshl_add_u64 v[66:67], s[22:23], 0, v[66:67]
	v_lshl_add_u64 v[66:67], s[34:35], 2, v[66:67]
	s_lshl_b32 s92, s45, 2
	v_lshl_add_u64 v[66:67], v[66:67], 0, s[92:93]
	global_store_dword v[66:67], v68, off
.LBB0_310:
	s_or_b64 exec, exec, s[0:1]
	v_lshlrev_b32_e32 v66, 16, v158
	s_waitcnt lgkmcnt(0)
	v_and_b32_e32 v67, 0xffff0000, v158
	v_lshlrev_b32_e32 v68, 16, v159
	v_and_b32_e32 v69, 0xffff0000, v159
	v_lshlrev_b32_e32 v70, 16, v160
	v_and_b32_e32 v71, 0xffff0000, v160
	v_lshlrev_b32_e32 v72, 16, v161
	v_and_b32_e32 v73, 0xffff0000, v161
	v_pk_add_f32 v[64:65], v[64:65], v[68:69]
	v_pk_add_f32 v[62:63], v[62:63], v[66:67]
	v_pk_add_f32 v[66:67], v[60:61], v[72:73]
	v_pk_add_f32 v[60:61], v[58:59], v[70:71]
	v_mul_f32_e32 v58, v63, v63
	v_mul_f32_e32 v59, v65, v65
	v_fmac_f32_e32 v58, v62, v62
	v_fmac_f32_e32 v59, v64, v64
	v_add_f32_e32 v58, v58, v59
	v_mul_f32_e32 v59, v61, v61
	v_fmac_f32_e32 v59, v60, v60
	v_add_f32_e32 v58, v59, v58
	v_mul_f32_e32 v59, v67, v67
	v_fmac_f32_e32 v59, v66, v66
	v_add_f32_e32 v70, v59, v58
	v_cvt_pk_bf16_f32 v58, v62, v63
	v_cvt_pk_bf16_f32 v59, v64, v65
	v_lshlrev_b32_e32 v62, 16, v154
	v_and_b32_e32 v63, 0xffff0000, v154
	v_lshlrev_b32_e32 v64, 16, v155
	v_and_b32_e32 v65, 0xffff0000, v155
	v_cvt_pk_bf16_f32 v60, v60, v61
	v_cvt_pk_bf16_f32 v61, v66, v67
	v_lshlrev_b32_e32 v66, 16, v156
	v_and_b32_e32 v67, 0xffff0000, v156
	v_pk_add_f32 v[56:57], v[56:57], v[64:65]
	v_pk_add_f32 v[54:55], v[54:55], v[62:63]
	v_pk_add_f32 v[64:65], v[50:51], v[66:67]
	v_mul_f32_e32 v50, v55, v55
	v_mul_f32_e32 v51, v57, v57
	v_fmac_f32_e32 v50, v54, v54
	v_fmac_f32_e32 v51, v56, v56
	v_lshlrev_b32_e32 v68, 16, v157
	v_and_b32_e32 v69, 0xffff0000, v157
	v_add_f32_e32 v50, v50, v51
	v_mul_f32_e32 v51, v65, v65
	v_pk_add_f32 v[62:63], v[52:53], v[68:69]
	v_fmac_f32_e32 v51, v64, v64
	v_add_f32_e32 v50, v51, v50
	v_mul_f32_e32 v51, v63, v63
	v_fmac_f32_e32 v51, v62, v62
	v_add_f32_e32 v50, v51, v50
	v_add_f32_e32 v53, v70, v50
	v_mov_b32_e32 v68, v53
	s_nop 1
	v_permlane16_swap_b32_e32 v53, v68
	v_lshl_add_u64 v[50:51], s[36:37], 0, v[228:229]
	v_lshl_add_u64 v[66:67], v[212:213], 1, v[50:51]
	global_store_dwordx4 v[66:67], v[58:61], off
	s_waitcnt lgkmcnt(0)
	v_add_f32_e32 v50, v53, v68
	v_mov_b32_e32 v51, v50
	s_nop 1
	v_permlane32_swap_b32_e32 v50, v51
	v_cvt_pk_bf16_f32 v52, v54, v55
	v_cvt_pk_bf16_f32 v53, v56, v57
	v_cvt_pk_bf16_f32 v54, v64, v65
	v_cvt_pk_bf16_f32 v55, v62, v63
	global_store_dwordx4 v[66:67], v[52:55], off offset:256
	s_and_saveexec_b64 s[0:1], vcc
	s_cbranch_execz .LBB0_312
	s_waitcnt lgkmcnt(0)
	v_add_f32_e32 v52, v50, v51
	v_lshlrev_b64 v[50:51], 6, v[226:227]
	v_lshl_add_u64 v[50:51], s[22:23], 0, v[50:51]
	v_lshl_add_u64 v[50:51], s[34:35], 2, v[50:51]
	s_lshl_b32 s92, s45, 2
	v_lshl_add_u64 v[50:51], v[50:51], 0, s[92:93]
	global_store_dword v[50:51], v52, off
; __device__ __forceinline__ unsigned cvt_pk_bf16(float lo, float hi) { unsigned r; asm("v_cvt_pk_bf16_f32 %0, %1, %2" : "=v"(r) : "v"(lo), "v"(hi)); return r; }
; __device__ __forceinline__ void unpack8(const u32x4 w, float (&f)[8]) { f[0] = bf_lo(w.x); f[1] = bf_hi(w.x); f[2] = bf_lo(w.y); f[3] = bf_hi(w.y); f[4] = bf_lo(w.z); f[5] = bf_hi(w.z); f[6] = bf_lo(w.w); f[7] = bf_hi(w.w); }
;     __device__ __forceinline__ void operator()(const f32x4 (&acc)[2][2][4][2], const Unit& u, int wr, int wc, int fr, int fq) const {
;     ...
;         for (int ai = 0; ai < 2; ++ai) {
; #pragma unroll
;             for (int m = 0; m < 4; ++m) { const int row = row0 + ai * HALF + m * 16; const size_t off = (size_t)row * D + col0; float sq = 0.f;
; #pragma unroll
;                 for (int bj = 0; bj < 2; ++bj) {
;                     float xf[8]; unpack8(xo[ai][m][bj], xf);
;                     const f32x4 x0 = (f32x4){xf[0], xf[1], xf[2], xf[3]} + acc[ai][bj][m][0], x1 = (f32x4){xf[4], xf[5], xf[6], xf[7]} + acc[ai][bj][m][1];
;                     sq += (x0[0] * x0[0] + x0[1] * x0[1]) + (x0[2] * x0[2] + x0[3] * x0[3]) + (x1[0] * x1[0] + x1[1] * x1[1]) + (x1[2] * x1[2] + x1[3] * x1[3]);
;                     u32x4 w; w.x = cvt_pk_bf16(x0[0], x0[1]); w.y = cvt_pk_bf16(x0[2], x0[3]); w.z = cvt_pk_bf16(x1[0], x1[1]); w.w = cvt_pk_bf16(x1[2], x1[3]);
;                     *(u32x4*)(xb + off + bj * HALF) = w; }
;                 sq += __shfl_xor(sq, 16); sq += __shfl_xor(sq, 32); if (fq == 0) ssn[(size_t)row * 16 + u.pn * 4 + wc] = sq; }
.LBB0_312:
	s_or_b64 exec, exec, s[0:1]
	v_lshlrev_b32_e32 v50, 16, v150
	s_waitcnt lgkmcnt(0)
	v_and_b32_e32 v51, 0xffff0000, v150
	v_lshlrev_b32_e32 v52, 16, v151
	v_and_b32_e32 v53, 0xffff0000, v151
	v_lshlrev_b32_e32 v54, 16, v152
	v_and_b32_e32 v55, 0xffff0000, v152
	v_lshlrev_b32_e32 v56, 16, v153
	v_and_b32_e32 v57, 0xffff0000, v153
	v_pk_add_f32 v[48:49], v[48:49], v[52:53]
	v_pk_add_f32 v[46:47], v[46:47], v[50:51]
	v_pk_add_f32 v[50:51], v[44:45], v[56:57]
	v_pk_add_f32 v[44:45], v[42:43], v[54:55]
	v_mul_f32_e32 v42, v47, v47
	v_mul_f32_e32 v43, v49, v49
	v_fmac_f32_e32 v42, v46, v46
	v_fmac_f32_e32 v43, v48, v48
	v_add_f32_e32 v42, v42, v43
	v_mul_f32_e32 v43, v45, v45
	v_fmac_f32_e32 v43, v44, v44
	v_add_f32_e32 v42, v43, v42
	v_mul_f32_e32 v43, v51, v51
	v_fmac_f32_e32 v43, v50, v50
	v_add_f32_e32 v54, v43, v42
	v_cvt_pk_bf16_f32 v42, v46, v47
	v_cvt_pk_bf16_f32 v43, v48, v49
	v_lshlrev_b32_e32 v46, 16, v146
	v_and_b32_e32 v47, 0xffff0000, v146
	v_lshlrev_b32_e32 v48, 16, v147
	v_and_b32_e32 v49, 0xffff0000, v147
	v_cvt_pk_bf16_f32 v44, v44, v45
	v_cvt_pk_bf16_f32 v45, v50, v51
	v_lshlrev_b32_e32 v50, 16, v148
	v_and_b32_e32 v51, 0xffff0000, v148
	v_pk_add_f32 v[40:41], v[40:41], v[48:49]
	v_pk_add_f32 v[38:39], v[38:39], v[46:47]
	v_pk_add_f32 v[48:49], v[34:35], v[50:51]
	v_mul_f32_e32 v34, v39, v39
	v_mul_f32_e32 v35, v41, v41
	v_fmac_f32_e32 v34, v38, v38
	v_fmac_f32_e32 v35, v40, v40
	v_lshlrev_b32_e32 v52, 16, v149
	v_and_b32_e32 v53, 0xffff0000, v149
	v_add_f32_e32 v34, v34, v35
	v_mul_f32_e32 v35, v49, v49
	v_pk_add_f32 v[46:47], v[36:37], v[52:53]
	v_fmac_f32_e32 v35, v48, v48
	v_add_f32_e32 v34, v35, v34
	v_mul_f32_e32 v35, v47, v47
	v_fmac_f32_e32 v35, v46, v46
	v_add_f32_e32 v34, v35, v34
	v_add_f32_e32 v37, v54, v34
	v_mov_b32_e32 v52, v37
	s_nop 1
	v_permlane16_swap_b32_e32 v37, v52
	v_lshl_add_u64 v[34:35], s[36:37], 0, v[224:225]
	v_lshl_add_u64 v[50:51], v[212:213], 1, v[34:35]
	global_store_dwordx4 v[50:51], v[42:45], off
	v_cvt_pk_bf16_f32 v36, v38, v39
	s_waitcnt lgkmcnt(0)
	v_add_f32_e32 v34, v37, v52
	v_mov_b32_e32 v35, v34
	s_nop 1
	v_permlane32_swap_b32_e32 v34, v35
	v_cvt_pk_bf16_f32 v37, v40, v41
	v_cvt_pk_bf16_f32 v38, v48, v49
	v_cvt_pk_bf16_f32 v39, v46, v47
	global_store_dwordx4 v[50:51], v[36:39], off offset:256
	s_and_saveexec_b64 s[0:1], vcc
	s_cbranch_execz .LBB0_314
	s_waitcnt lgkmcnt(0)
	v_add_f32_e32 v36, v34, v35
	v_lshlrev_b64 v[34:35], 6, v[222:223]
	v_lshl_add_u64 v[34:35], s[22:23], 0, v[34:35]
	v_lshl_add_u64 v[34:35], s[34:35], 2, v[34:35]
	s_lshl_b32 s92, s45, 2
	v_lshl_add_u64 v[34:35], v[34:35], 0, s[92:93]
	global_store_dword v[34:35], v36, off
; __device__ __forceinline__ unsigned cvt_pk_bf16(float lo, float hi) { unsigned r; asm("v_cvt_pk_bf16_f32 %0, %1, %2" : "=v"(r) : "v"(lo), "v"(hi)); return r; }
; __device__ __forceinline__ void unpack8(const u32x4 w, float (&f)[8]) { f[0] = bf_lo(w.x); f[1] = bf_hi(w.x); f[2] = bf_lo(w.y); f[3] = bf_hi(w.y); f[4] = bf_lo(w.z); f[5] = bf_hi(w.z); f[6] = bf_lo(w.w); f[7] = bf_hi(w.w); }
;     __device__ __forceinline__ void operator()(const f32x4 (&acc)[2][2][4][2], const Unit& u, int wr, int wc, int fr, int fq) const {
;     ...
;         for (int ai = 0; ai < 2; ++ai) {
; #pragma unroll
;             for (int m = 0; m < 4; ++m) { const int row = row0 + ai * HALF + m * 16; const size_t off = (size_t)row * D + col0; float sq = 0.f;
; #pragma unroll
;                 for (int bj = 0; bj < 2; ++bj) {
;                     float xf[8]; unpack8(xo[ai][m][bj], xf);
;                     const f32x4 x0 = (f32x4){xf[0], xf[1], xf[2], xf[3]} + acc[ai][bj][m][0], x1 = (f32x4){xf[4], xf[5], xf[6], xf[7]} + acc[ai][bj][m][1];
;                     sq += (x0[0] * x0[0] + x0[1] * x0[1]) + (x0[2] * x0[2] + x0[3] * x0[3]) + (x1[0] * x1[0] + x1[1] * x1[1]) + (x1[2] * x1[2] + x1[3] * x1[3]);
;                     u32x4 w; w.x = cvt_pk_bf16(x0[0], x0[1]); w.y = cvt_pk_bf16(x0[2], x0[3]); w.z = cvt_pk_bf16(x1[0], x1[1]); w.w = cvt_pk_bf16(x1[2], x1[3]);
;                     *(u32x4*)(xb + off + bj * HALF) = w; }
;                 sq += __shfl_xor(sq, 16); sq += __shfl_xor(sq, 32); if (fq == 0) ssn[(size_t)row * 16 + u.pn * 4 + wc] = sq; }
.LBB0_314:
	s_or_b64 exec, exec, s[0:1]
	v_lshlrev_b32_e32 v34, 16, v142
	s_waitcnt lgkmcnt(0)
	v_and_b32_e32 v35, 0xffff0000, v142
	v_lshlrev_b32_e32 v36, 16, v143
	v_and_b32_e32 v37, 0xffff0000, v143
	v_lshlrev_b32_e32 v38, 16, v144
	v_and_b32_e32 v39, 0xffff0000, v144
	v_lshlrev_b32_e32 v40, 16, v145
	v_and_b32_e32 v41, 0xffff0000, v145
	v_pk_add_f32 v[32:33], v[32:33], v[36:37]
	v_pk_add_f32 v[30:31], v[30:31], v[34:35]
	v_pk_add_f32 v[34:35], v[28:29], v[40:41]
	v_pk_add_f32 v[28:29], v[26:27], v[38:39]
	v_mul_f32_e32 v26, v31, v31
	v_mul_f32_e32 v27, v33, v33
	v_fmac_f32_e32 v26, v30, v30
	v_fmac_f32_e32 v27, v32, v32
	v_add_f32_e32 v26, v26, v27
	v_mul_f32_e32 v27, v29, v29
	v_fmac_f32_e32 v27, v28, v28
	v_add_f32_e32 v26, v27, v26
	v_mul_f32_e32 v27, v35, v35
	v_fmac_f32_e32 v27, v34, v34
	v_add_f32_e32 v38, v27, v26
	v_cvt_pk_bf16_f32 v26, v30, v31
	v_cvt_pk_bf16_f32 v27, v32, v33
	v_lshlrev_b32_e32 v30, 16, v134
	v_and_b32_e32 v31, 0xffff0000, v134
	v_lshlrev_b32_e32 v32, 16, v135
	v_and_b32_e32 v33, 0xffff0000, v135
	v_cvt_pk_bf16_f32 v28, v28, v29
	v_cvt_pk_bf16_f32 v29, v34, v35
	v_lshlrev_b32_e32 v34, 16, v136
	v_and_b32_e32 v35, 0xffff0000, v136
	v_pk_add_f32 v[24:25], v[24:25], v[32:33]
	v_pk_add_f32 v[22:23], v[22:23], v[30:31]
	v_pk_add_f32 v[32:33], v[18:19], v[34:35]
	v_mul_f32_e32 v18, v23, v23
	v_mul_f32_e32 v19, v25, v25
	v_fmac_f32_e32 v18, v22, v22
	v_fmac_f32_e32 v19, v24, v24
	v_lshlrev_b32_e32 v36, 16, v137
	v_and_b32_e32 v37, 0xffff0000, v137
	v_add_f32_e32 v18, v18, v19
	v_mul_f32_e32 v19, v33, v33
	v_pk_add_f32 v[30:31], v[20:21], v[36:37]
	v_fmac_f32_e32 v19, v32, v32
	v_add_f32_e32 v18, v19, v18
	v_mul_f32_e32 v19, v31, v31
	v_fmac_f32_e32 v19, v30, v30
	v_add_f32_e32 v18, v19, v18
	v_add_f32_e32 v21, v38, v18
	v_mov_b32_e32 v36, v21
	s_nop 1
	v_permlane16_swap_b32_e32 v21, v36
	v_lshl_add_u64 v[18:19], s[36:37], 0, v[220:221]
	v_lshl_add_u64 v[34:35], v[212:213], 1, v[18:19]
	global_store_dwordx4 v[34:35], v[26:29], off
	v_cvt_pk_bf16_f32 v20, v22, v23
	s_waitcnt lgkmcnt(0)
	v_add_f32_e32 v18, v21, v36
	v_mov_b32_e32 v19, v18
	s_nop 1
	v_permlane32_swap_b32_e32 v18, v19
	v_cvt_pk_bf16_f32 v21, v24, v25
	v_cvt_pk_bf16_f32 v22, v32, v33
	v_cvt_pk_bf16_f32 v23, v30, v31
	global_store_dwordx4 v[34:35], v[20:23], off offset:256
	s_and_saveexec_b64 s[0:1], vcc
	s_cbranch_execz .LBB0_316
	s_waitcnt lgkmcnt(0)
	v_add_f32_e32 v20, v18, v19
	v_lshlrev_b64 v[18:19], 6, v[218:219]
	v_lshl_add_u64 v[18:19], s[22:23], 0, v[18:19]
	v_lshl_add_u64 v[18:19], s[34:35], 2, v[18:19]
	s_lshl_b32 s92, s45, 2
	v_lshl_add_u64 v[18:19], v[18:19], 0, s[92:93]
	global_store_dword v[18:19], v20, off
.LBB0_316:
	s_or_b64 exec, exec, s[0:1]
	v_lshlrev_b32_e32 v18, 16, v138
	s_waitcnt lgkmcnt(0)
	v_and_b32_e32 v19, 0xffff0000, v138
	v_lshlrev_b32_e32 v20, 16, v139
	v_and_b32_e32 v21, 0xffff0000, v139
	v_lshlrev_b32_e32 v22, 16, v140
	v_and_b32_e32 v23, 0xffff0000, v140
	v_lshlrev_b32_e32 v24, 16, v141
	v_and_b32_e32 v25, 0xffff0000, v141
	v_pk_add_f32 v[16:17], v[16:17], v[20:21]
	v_pk_add_f32 v[14:15], v[14:15], v[18:19]
	v_pk_add_f32 v[18:19], v[12:13], v[24:25]
	v_pk_add_f32 v[12:13], v[10:11], v[22:23]
	v_mul_f32_e32 v10, v15, v15
	v_mul_f32_e32 v11, v17, v17
	v_fmac_f32_e32 v10, v14, v14
	v_fmac_f32_e32 v11, v16, v16
	v_add_f32_e32 v10, v10, v11
	v_mul_f32_e32 v11, v13, v13
	v_fmac_f32_e32 v11, v12, v12
	v_add_f32_e32 v10, v11, v10
	v_mul_f32_e32 v11, v19, v19
	v_fmac_f32_e32 v11, v18, v18
	v_add_f32_e32 v22, v11, v10
	v_cvt_pk_bf16_f32 v10, v14, v15
	v_cvt_pk_bf16_f32 v11, v16, v17
	v_lshlrev_b32_e32 v14, 16, v130
	v_and_b32_e32 v15, 0xffff0000, v130
	v_lshlrev_b32_e32 v16, 16, v131
	v_and_b32_e32 v17, 0xffff0000, v131
	v_cvt_pk_bf16_f32 v12, v12, v13
	v_cvt_pk_bf16_f32 v13, v18, v19
	v_lshlrev_b32_e32 v18, 16, v132
	v_and_b32_e32 v19, 0xffff0000, v132
	v_pk_add_f32 v[8:9], v[8:9], v[16:17]
	v_pk_add_f32 v[6:7], v[6:7], v[14:15]
	v_pk_add_f32 v[16:17], v[2:3], v[18:19]
	v_mul_f32_e32 v2, v7, v7
	v_mul_f32_e32 v3, v9, v9
	v_fmac_f32_e32 v2, v6, v6
	v_fmac_f32_e32 v3, v8, v8
	v_lshlrev_b32_e32 v20, 16, v133
	v_and_b32_e32 v21, 0xffff0000, v133
	v_add_f32_e32 v2, v2, v3
	v_mul_f32_e32 v3, v17, v17
	v_pk_add_f32 v[14:15], v[4:5], v[20:21]
	v_fmac_f32_e32 v3, v16, v16
	v_add_f32_e32 v2, v3, v2
	v_mul_f32_e32 v3, v15, v15
	v_fmac_f32_e32 v3, v14, v14
	v_add_f32_e32 v2, v3, v2
	v_add_f32_e32 v5, v22, v2
	v_mov_b32_e32 v20, v5
	s_nop 1
	v_permlane16_swap_b32_e32 v5, v20
	v_lshl_add_u64 v[2:3], s[36:37], 0, v[216:217]
	v_lshl_add_u64 v[18:19], v[212:213], 1, v[2:3]
	global_store_dwordx4 v[18:19], v[10:13], off
	v_cvt_pk_bf16_f32 v4, v6, v7
	s_waitcnt lgkmcnt(0)
	v_add_f32_e32 v2, v5, v20
	v_mov_b32_e32 v3, v2
	s_nop 1
	v_permlane32_swap_b32_e32 v2, v3
	v_cvt_pk_bf16_f32 v5, v8, v9
	v_cvt_pk_bf16_f32 v6, v16, v17
	v_cvt_pk_bf16_f32 v7, v14, v15
	global_store_dwordx4 v[18:19], v[4:7], off offset:256
	s_and_saveexec_b64 s[0:1], vcc
	s_cbranch_execz .LBB0_318
	s_waitcnt lgkmcnt(0)
	v_add_f32_e32 v4, v2, v3
	v_lshlrev_b64 v[2:3], 6, v[214:215]
	v_lshl_add_u64 v[2:3], s[22:23], 0, v[2:3]
	v_lshl_add_u64 v[2:3], s[34:35], 2, v[2:3]
	s_lshl_b32 s92, s45, 2
	v_lshl_add_u64 v[2:3], v[2:3], 0, s[92:93]
	global_store_dword v[2:3], v4, off
